# on top of the combined version: in phase 4 the chunk_pre blocks that own 4 units run at priority 1, the ones that own 5 stay at 2
# baseline (speedup 1.0000x reference)
.LBB0_639:
	s_setprio 2
	s_cmp_lt_u32 s2, 0x140
	s_cbranch_scc1 .Lp4f
	s_setprio 1
